# k26a + GU GEMM loop: 16 per-segment s_setprio flips deleted, one static s_setprio 1 for waves 4-7 before the K loop, reset after
# speedup vs baseline: 1.0101x; 1.0035x over previous
; #define PG8_BAR __builtin_amdgcn_s_barrier()
; template <class Epi>
; __device__ __forceinline__ void gemm_phase(PG8_LAS unsigned char* lds, const Gemm g, const StaticOrder& S, const Epi& E, const int wave_s) {
;     ...
;         const bool has_next = S.next(ui + 1, nxt);
;         const char* nA = has_next ? (const char*)g.A + (size_t)nxt.pm * tstepA : cA; const char* nB = has_next ? (const char*)g.Bt + (size_t)nxt.pn * tstepB : cB;
;         float pre[8]; E.prefetch(cur, wr, fr, pre);
;         for (int t = 0; t < nt; t += 2) {
;             const bool last = (t == nt - 2);
;             const char* a1 = cA + (size_t)(t + 1) * kstep;
;             const char* a2 = last ? nA : cA + (size_t)(t + 2) * kstep; const char* b2 = last ? nB : cB + (size_t)(t + 2) * kstep;
;             const char* a3 = a2 + kstep; const char* b3 = b2 + kstep;
;             PG8_LDB(B0, 0, 0); PG8_LDB(B1, 0, 1); PG8_SCHED; PG8_LDA(At, 0, 0); PG8_STAGE(PG8_SA(1, 1), a1 + hstepA, voffA);
;             PG8_WAIT_V(8); PG8_WAIT_L(0); PG8_BAR; PG8_MMA(0, 0, At, B0); PG8_MMA(0, 1, At, B1); PG8_BAR; PG8_SCHED;
;             PG8_LDA(At, 0, 1); PG8_STAGE(PG8_SB(0, 0), b2, voffB); PG8_STAGE(PG8_SB(0, 1), b2 + hstepB, voffB); PG8_STAGE(PG8_SA(0, 0), a2, voffA);
;             PG8_WAIT_V(8); PG8_WAIT_L(0); PG8_BAR; PG8_MMA(1, 0, At, B0); PG8_MMA(1, 1, At, B1); PG8_BAR; PG8_SCHED;
;             PG8_LDB(B0, 1, 0); PG8_LDB(B1, 1, 1); PG8_SCHED; PG8_LDA(At, 1, 0); PG8_STAGE(PG8_SA(0, 1), a2 + hstepA, voffA);
;             PG8_WAIT_V(8); PG8_WAIT_L(0); PG8_BAR; PG8_MMA(0, 0, At, B0); PG8_MMA(0, 1, At, B1); PG8_BAR; PG8_SCHED;
;             PG8_LDA(At, 1, 1); PG8_STAGE(PG8_SB(1, 0), b3, voffB); PG8_STAGE(PG8_SB(1, 1), b3 + hstepB, voffB); PG8_STAGE(PG8_SA(1, 0), a3, voffA);
;             PG8_WAIT_V(8); PG8_WAIT_L(0); PG8_BAR; PG8_MMA(1, 0, At, B0); PG8_MMA(1, 1, At, B1); PG8_BAR; PG8_SCHED;
;         }
;         if (wr == 0) PG8_BAR;
;         { const int tl = fresh_tid(wave_s); const int w2 = wave_s, l2 = tl & 63;
;           E(acc, cur, w2 >> 2, w2 & 3, l2 & 15, l2 >> 4, pre); }
;         if (!has_next) break;
; #pragma unroll
;         for (int a = 0; a < 2; ++a)
; #pragma unroll
;             for (int b = 0; b < 2; ++b)
; #pragma unroll
;                 for (int m = 0; m < 4; ++m)
; #pragma unroll
;                     for (int n = 0; n < 2; ++n) acc[a][b][m][n] = (f32x4){0.f, 0.f, 0.f, 0.f};
.LBB0_948:
	s_lshl_b32 s65, s65, 8
	v_add_u32_e32 v0, s65, v97
	v_ashrrev_i32_e32 v1, 31, v0
	v_lshl_add_u64 v[0:1], v[0:1], 2, s[30:31]
	global_load_dword v154, v[0:1], off
	global_load_dword v152, v[0:1], off offset:64
	global_load_dword v150, v[0:1], off offset:128
	global_load_dword v148, v[0:1], off offset:192
	global_load_dword v146, v[0:1], off offset:512
	global_load_dword v144, v[0:1], off offset:576
	global_load_dword v142, v[0:1], off offset:640
	global_load_dword v140, v[0:1], off offset:704
	v_mov_b32_e32 v129, 0
	s_andn2_b64 vcc, exec, s[46:47]
	v_mov_b32_e32 v128, v129
	v_mov_b32_e32 v127, v129
	v_mov_b32_e32 v126, v129
	v_mov_b32_e32 v125, v129
	v_mov_b32_e32 v124, v129
	v_mov_b32_e32 v123, v129
	v_mov_b32_e32 v122, v129
	v_mov_b32_e32 v113, v129
	v_mov_b32_e32 v112, v129
	v_mov_b32_e32 v111, v129
	v_mov_b32_e32 v110, v129
	v_mov_b32_e32 v109, v129
	v_mov_b32_e32 v108, v129
	v_mov_b32_e32 v107, v129
	v_mov_b32_e32 v106, v129
	v_mov_b32_e32 v95, v129
	v_mov_b32_e32 v94, v129
	v_mov_b32_e32 v93, v129
	v_mov_b32_e32 v92, v129
	v_mov_b32_e32 v91, v129
	v_mov_b32_e32 v90, v129
	v_mov_b32_e32 v89, v129
	v_mov_b32_e32 v88, v129
	v_mov_b32_e32 v79, v129
	v_mov_b32_e32 v78, v129
	v_mov_b32_e32 v77, v129
	v_mov_b32_e32 v76, v129
	v_mov_b32_e32 v75, v129
	v_mov_b32_e32 v74, v129
	v_mov_b32_e32 v73, v129
	v_mov_b32_e32 v72, v129
	v_mov_b32_e32 v121, v129
	v_mov_b32_e32 v120, v129
	v_mov_b32_e32 v119, v129
	v_mov_b32_e32 v118, v129
	v_mov_b32_e32 v117, v129
	v_mov_b32_e32 v116, v129
	v_mov_b32_e32 v115, v129
	v_mov_b32_e32 v114, v129
	v_mov_b32_e32 v105, v129
	v_mov_b32_e32 v104, v129
	v_mov_b32_e32 v103, v129
	v_mov_b32_e32 v102, v129
	v_mov_b32_e32 v101, v129
	v_mov_b32_e32 v100, v129
	v_mov_b32_e32 v99, v129
	v_mov_b32_e32 v98, v129
	v_mov_b32_e32 v87, v129
	v_mov_b32_e32 v86, v129
	v_mov_b32_e32 v85, v129
	v_mov_b32_e32 v84, v129
	v_mov_b32_e32 v83, v129
	v_mov_b32_e32 v82, v129
	v_mov_b32_e32 v81, v129
	v_mov_b32_e32 v80, v129
	v_mov_b32_e32 v71, v129
	v_mov_b32_e32 v70, v129
	v_mov_b32_e32 v69, v129
	v_mov_b32_e32 v68, v129
	v_mov_b32_e32 v67, v129
	v_mov_b32_e32 v66, v129
	v_mov_b32_e32 v65, v129
	v_mov_b32_e32 v64, v129
	v_mov_b32_e32 v63, v129
	v_mov_b32_e32 v62, v129
	v_mov_b32_e32 v61, v129
	v_mov_b32_e32 v60, v129
	v_mov_b32_e32 v59, v129
	v_mov_b32_e32 v58, v129
	v_mov_b32_e32 v57, v129
	v_mov_b32_e32 v56, v129
	v_mov_b32_e32 v47, v129
	v_mov_b32_e32 v46, v129
	v_mov_b32_e32 v45, v129
	v_mov_b32_e32 v44, v129
	v_mov_b32_e32 v43, v129
	v_mov_b32_e32 v42, v129
	v_mov_b32_e32 v41, v129
	v_mov_b32_e32 v40, v129
	v_mov_b32_e32 v31, v129
	v_mov_b32_e32 v30, v129
	v_mov_b32_e32 v29, v129
	v_mov_b32_e32 v28, v129
	v_mov_b32_e32 v27, v129
	v_mov_b32_e32 v26, v129
	v_mov_b32_e32 v25, v129
	v_mov_b32_e32 v24, v129
	v_mov_b32_e32 v15, v129
	v_mov_b32_e32 v14, v129
	v_mov_b32_e32 v13, v129
	v_mov_b32_e32 v12, v129
	v_mov_b32_e32 v11, v129
	v_mov_b32_e32 v10, v129
	v_mov_b32_e32 v9, v129
	v_mov_b32_e32 v8, v129
	v_mov_b32_e32 v55, v129
	v_mov_b32_e32 v54, v129
	v_mov_b32_e32 v53, v129
	v_mov_b32_e32 v52, v129
	v_mov_b32_e32 v51, v129
	v_mov_b32_e32 v50, v129
	v_mov_b32_e32 v49, v129
	v_mov_b32_e32 v48, v129
	v_mov_b32_e32 v39, v129
	v_mov_b32_e32 v38, v129
	v_mov_b32_e32 v37, v129
	v_mov_b32_e32 v36, v129
	v_mov_b32_e32 v35, v129
	v_mov_b32_e32 v34, v129
	v_mov_b32_e32 v33, v129
	v_mov_b32_e32 v32, v129
	v_mov_b32_e32 v23, v129
	v_mov_b32_e32 v22, v129
	v_mov_b32_e32 v21, v129
	v_mov_b32_e32 v20, v129
	v_mov_b32_e32 v19, v129
	v_mov_b32_e32 v18, v129
	v_mov_b32_e32 v17, v129
	v_mov_b32_e32 v16, v129
	v_mov_b32_e32 v7, v129
	v_mov_b32_e32 v6, v129
	v_mov_b32_e32 v5, v129
	v_mov_b32_e32 v4, v129
	v_mov_b32_e32 v3, v129
	v_mov_b32_e32 v2, v129
	v_mov_b32_e32 v1, v129
	v_mov_b32_e32 v0, v129
	s_cbranch_vccnz .LBB0_951
	s_add_u32 s56, s56, 0x80
	s_addc_u32 s57, s57, 0
	s_add_u32 s66, s6, 0x100
	v_mov_b32_e32 v0, 0
	s_addc_u32 s67, s7, 0
	s_mov_b32 s6, 0
	v_mov_b32_e32 v1, v0
	v_mov_b32_e32 v2, v0
	v_mov_b32_e32 v3, v0
	v_mov_b32_e32 v4, v0
	v_mov_b32_e32 v5, v0
	v_mov_b32_e32 v6, v0
	v_mov_b32_e32 v7, v0
	v_mov_b32_e32 v16, v0
	v_mov_b32_e32 v17, v0
	v_mov_b32_e32 v18, v0
	v_mov_b32_e32 v19, v0
	v_mov_b32_e32 v20, v0
	v_mov_b32_e32 v21, v0
	v_mov_b32_e32 v22, v0
	v_mov_b32_e32 v23, v0
	v_mov_b32_e32 v32, v0
	v_mov_b32_e32 v33, v0
	v_mov_b32_e32 v34, v0
	v_mov_b32_e32 v35, v0
	v_mov_b32_e32 v36, v0
	v_mov_b32_e32 v37, v0
	v_mov_b32_e32 v38, v0
	v_mov_b32_e32 v39, v0
	v_mov_b32_e32 v48, v0
	v_mov_b32_e32 v49, v0
	v_mov_b32_e32 v50, v0
	v_mov_b32_e32 v51, v0
	v_mov_b32_e32 v52, v0
	v_mov_b32_e32 v53, v0
	v_mov_b32_e32 v54, v0
	v_mov_b32_e32 v55, v0
	v_mov_b32_e32 v8, v0
	v_mov_b32_e32 v9, v0
	v_mov_b32_e32 v10, v0
	v_mov_b32_e32 v11, v0
	v_mov_b32_e32 v12, v0
	v_mov_b32_e32 v13, v0
	v_mov_b32_e32 v14, v0
	v_mov_b32_e32 v15, v0
	v_mov_b32_e32 v24, v0
	v_mov_b32_e32 v25, v0
	v_mov_b32_e32 v26, v0
	v_mov_b32_e32 v27, v0
	v_mov_b32_e32 v28, v0
	v_mov_b32_e32 v29, v0
	v_mov_b32_e32 v30, v0
	v_mov_b32_e32 v31, v0
	v_mov_b32_e32 v40, v0
	v_mov_b32_e32 v41, v0
	v_mov_b32_e32 v42, v0
	v_mov_b32_e32 v43, v0
	v_mov_b32_e32 v44, v0
	v_mov_b32_e32 v45, v0
	v_mov_b32_e32 v46, v0
	v_mov_b32_e32 v47, v0
	v_mov_b32_e32 v56, v0
	v_mov_b32_e32 v57, v0
	v_mov_b32_e32 v58, v0
	v_mov_b32_e32 v59, v0
	v_mov_b32_e32 v60, v0
	v_mov_b32_e32 v61, v0
	v_mov_b32_e32 v62, v0
	v_mov_b32_e32 v63, v0
	v_mov_b32_e32 v64, v0
	v_mov_b32_e32 v65, v0
	v_mov_b32_e32 v66, v0
	v_mov_b32_e32 v67, v0
	v_mov_b32_e32 v68, v0
	v_mov_b32_e32 v69, v0
	v_mov_b32_e32 v70, v0
	v_mov_b32_e32 v71, v0
	v_mov_b32_e32 v80, v0
	v_mov_b32_e32 v81, v0
	v_mov_b32_e32 v82, v0
	v_mov_b32_e32 v83, v0
	v_mov_b32_e32 v84, v0
	v_mov_b32_e32 v85, v0
	v_mov_b32_e32 v86, v0
	v_mov_b32_e32 v87, v0
	v_mov_b32_e32 v98, v0
	v_mov_b32_e32 v99, v0
	v_mov_b32_e32 v100, v0
	v_mov_b32_e32 v101, v0
	v_mov_b32_e32 v102, v0
	v_mov_b32_e32 v103, v0
	v_mov_b32_e32 v104, v0
	v_mov_b32_e32 v105, v0
	v_mov_b32_e32 v114, v0
	v_mov_b32_e32 v115, v0
	v_mov_b32_e32 v116, v0
	v_mov_b32_e32 v117, v0
	v_mov_b32_e32 v118, v0
	v_mov_b32_e32 v119, v0
	v_mov_b32_e32 v120, v0
	v_mov_b32_e32 v121, v0
	v_mov_b32_e32 v72, v0
	v_mov_b32_e32 v73, v0
	v_mov_b32_e32 v74, v0
	v_mov_b32_e32 v75, v0
	v_mov_b32_e32 v76, v0
	v_mov_b32_e32 v77, v0
	v_mov_b32_e32 v78, v0
	v_mov_b32_e32 v79, v0
	v_mov_b32_e32 v88, v0
	v_mov_b32_e32 v89, v0
	v_mov_b32_e32 v90, v0
	v_mov_b32_e32 v91, v0
	v_mov_b32_e32 v92, v0
	v_mov_b32_e32 v93, v0
	v_mov_b32_e32 v94, v0
	v_mov_b32_e32 v95, v0
	v_mov_b32_e32 v106, v0
	v_mov_b32_e32 v107, v0
	v_mov_b32_e32 v108, v0
	v_mov_b32_e32 v109, v0
	v_mov_b32_e32 v110, v0
	v_mov_b32_e32 v111, v0
	v_mov_b32_e32 v112, v0
	v_mov_b32_e32 v113, v0
	v_mov_b32_e32 v122, v0
	v_mov_b32_e32 v123, v0
	v_mov_b32_e32 v124, v0
	v_mov_b32_e32 v125, v0
	v_mov_b32_e32 v126, v0
	v_mov_b32_e32 v127, v0
	v_mov_b32_e32 v128, v0
	v_mov_b32_e32 v129, v0
	v_readlane_b32 s7, v254, 61
	s_nop 3
	s_cmp_lt_u32 s7, 0x100
	s_cbranch_scc1 .Lgu_prio_done
	s_setprio 1
; #define PG8_STAGE(bufoff, gbase, voff) do { _Pragma("unroll") for (int _i = 0; _i < 2; ++_i) \
;         __builtin_amdgcn_global_load_lds((const unsigned*)((const char*)(gbase) + (voff)[_i]), (PG8_LAS unsigned*)(lds + (bufoff) + ldsw + _i * 8192), 16, 0, 0); } while (0)
; #define PG8_LDA(dst, b, h) do { _Pragma("unroll") for (int m = 0; m < 4; ++m) _Pragma("unroll") for (int k = 0; k < 2; ++k) dst[m][k] = *(const PG8_LAS bf16x8*)(lds + PG8_SA(b, h) + aoff + m * 2048 + k * 1024); } while (0)
; #define PG8_LDB(dst, b, h) do { _Pragma("unroll") for (int n = 0; n < 2; ++n) _Pragma("unroll") for (int k = 0; k < 2; ++k) dst[n][k] = *(const PG8_LAS bf16x8*)(lds + PG8_SB(b, h) + boff + n * 2048 + k * 1024); } while (0)
; #define PG8_MMA(ai, bj, At, Bt) do { __builtin_amdgcn_s_setprio(1); _Pragma("unroll") for (int m = 0; m < 4; ++m) _Pragma("unroll") for (int n = 0; n < 2; ++n) _Pragma("unroll") for (int k = 0; k < 2; ++k) \
;         acc[ai][bj][m][n] = __builtin_amdgcn_mfma_f32_16x16x32_bf16(Bt[n][k], At[m][k], acc[ai][bj][m][n], 0, 0, 0); __builtin_amdgcn_s_setprio(0); } while (0)
; #define PG8_WAIT_V(n) asm volatile("s_waitcnt vmcnt(" #n ")" ::: "memory")
; #define PG8_WAIT_L(n) asm volatile("s_waitcnt lgkmcnt(" #n ")" ::: "memory")
; #define PG8_BAR __builtin_amdgcn_s_barrier()
; #define PG8_SCHED __builtin_amdgcn_sched_barrier(0)
; template <class Epi>
; __device__ __forceinline__ void gemm_phase(PG8_LAS unsigned char* lds, const Gemm g, const StaticOrder& S, const Epi& E, const int wave_s) {
;     ...
;         for (int t = 0; t < nt; t += 2) {
;             const bool last = (t == nt - 2);
;             const char* a1 = cA + (size_t)(t + 1) * kstep;
;             const char* a2 = last ? nA : cA + (size_t)(t + 2) * kstep; const char* b2 = last ? nB : cB + (size_t)(t + 2) * kstep;
;             const char* a3 = a2 + kstep; const char* b3 = b2 + kstep;
;             PG8_LDB(B0, 0, 0); PG8_LDB(B1, 0, 1); PG8_SCHED; PG8_LDA(At, 0, 0); PG8_STAGE(PG8_SA(1, 1), a1 + hstepA, voffA);
;             PG8_WAIT_V(8); PG8_WAIT_L(0); PG8_BAR; PG8_MMA(0, 0, At, B0); PG8_MMA(0, 1, At, B1); PG8_BAR; PG8_SCHED;
;             PG8_LDA(At, 0, 1); PG8_STAGE(PG8_SB(0, 0), b2, voffB); PG8_STAGE(PG8_SB(0, 1), b2 + hstepB, voffB); PG8_STAGE(PG8_SA(0, 0), a2, voffA);
;             PG8_WAIT_V(8); PG8_WAIT_L(0); PG8_BAR; PG8_MMA(1, 0, At, B0); PG8_MMA(1, 1, At, B1); PG8_BAR; PG8_SCHED;
.Lgu_prio_done:
.LBB0_950:
	s_add_i32 s68, s6, 2
	s_add_u32 s69, s56, 0x80
	s_addc_u32 s7, s57, 0
	s_add_i32 s72, 0, 0x10000
	s_cmp_eq_u32 s60, s6
	s_cselect_b32 s7, s45, s7
	s_cselect_b32 s6, s44, s69
	v_add_u32_e32 v145, s72, v141
	s_cselect_b32 s71, s51, s67
	s_cselect_b32 s70, s50, s66
	s_add_i32 s69, 0, 0x14000
	ds_read_b128 v[156:159], v145
	ds_read_b128 v[160:163], v145 offset:1024
	ds_read_b128 v[164:167], v145 offset:2048
	ds_read_b128 v[168:171], v145 offset:3072
	v_add_u32_e32 v145, s69, v141
	ds_read_b128 v[172:175], v145
	ds_read_b128 v[176:179], v145 offset:1024
	ds_read_b128 v[180:183], v145 offset:2048
	ds_read_b128 v[184:187], v145 offset:3072
	v_lshl_add_u64 v[208:209], s[56:57], 0, v[136:137]
	s_add_i32 m0, s13, 0xc000
	ds_read_b128 v[188:191], v143
	ds_read_b128 v[192:195], v143 offset:1024
	ds_read_b128 v[196:199], v143 offset:2048
	ds_read_b128 v[200:203], v143 offset:3072
	ds_read_b128 v[204:207], v143 offset:4096
	ds_read_b128 v[218:221], v143 offset:5120
	ds_read_b128 v[222:225], v143 offset:6144
	ds_read_b128 v[226:229], v143 offset:7168
	global_load_lds_dwordx4 v[208:209], off
	v_lshl_add_u64 v[208:209], s[56:57], 0, v[138:139]
	s_add_i32 m0, s13, 0xe000
	s_nop 0
	global_load_lds_dwordx4 v[208:209], off
	s_waitcnt vmcnt(8)
	s_waitcnt lgkmcnt(0)
	s_barrier
	s_waitcnt lgkmcnt(0)
	v_mfma_f32_16x16x32_bf16 v[126:129], v[156:159], v[188:191], v[126:129]
	v_mfma_f32_16x16x32_bf16 v[122:125], v[164:167], v[188:191], v[122:125]
	v_mfma_f32_16x16x32_bf16 v[110:113], v[156:159], v[196:199], v[110:113]
	v_mfma_f32_16x16x32_bf16 v[106:109], v[164:167], v[196:199], v[106:109]
	v_mfma_f32_16x16x32_bf16 v[92:95], v[156:159], v[204:207], v[92:95]
	v_mfma_f32_16x16x32_bf16 v[88:91], v[164:167], v[204:207], v[88:91]
	v_mfma_f32_16x16x32_bf16 v[76:79], v[156:159], v[222:225], v[76:79]
	v_mfma_f32_16x16x32_bf16 v[72:75], v[164:167], v[222:225], v[72:75]
	v_mfma_f32_16x16x32_bf16 v[126:129], v[160:163], v[192:195], v[126:129]
	v_mfma_f32_16x16x32_bf16 v[122:125], v[168:171], v[192:195], v[122:125]
	v_mfma_f32_16x16x32_bf16 v[110:113], v[160:163], v[200:203], v[110:113]
	v_mfma_f32_16x16x32_bf16 v[106:109], v[168:171], v[200:203], v[106:109]
	v_mfma_f32_16x16x32_bf16 v[92:95], v[160:163], v[218:221], v[92:95]
	v_mfma_f32_16x16x32_bf16 v[88:91], v[168:171], v[218:221], v[88:91]
	v_mfma_f32_16x16x32_bf16 v[76:79], v[160:163], v[226:229], v[76:79]
	v_mfma_f32_16x16x32_bf16 v[72:75], v[168:171], v[226:229], v[72:75]
	v_mfma_f32_16x16x32_bf16 v[118:121], v[172:175], v[188:191], v[118:121]
	v_mfma_f32_16x16x32_bf16 v[114:117], v[180:183], v[188:191], v[114:117]
	v_mfma_f32_16x16x32_bf16 v[102:105], v[172:175], v[196:199], v[102:105]
	v_mfma_f32_16x16x32_bf16 v[98:101], v[180:183], v[196:199], v[98:101]
	v_mfma_f32_16x16x32_bf16 v[84:87], v[172:175], v[204:207], v[84:87]
	v_mfma_f32_16x16x32_bf16 v[80:83], v[180:183], v[204:207], v[80:83]
	v_mfma_f32_16x16x32_bf16 v[68:71], v[172:175], v[222:225], v[68:71]
	v_mfma_f32_16x16x32_bf16 v[64:67], v[180:183], v[222:225], v[64:67]
	v_mfma_f32_16x16x32_bf16 v[118:121], v[176:179], v[192:195], v[118:121]
	v_mfma_f32_16x16x32_bf16 v[114:117], v[184:187], v[192:195], v[114:117]
	v_mfma_f32_16x16x32_bf16 v[102:105], v[176:179], v[200:203], v[102:105]
	v_mfma_f32_16x16x32_bf16 v[98:101], v[184:187], v[200:203], v[98:101]
	v_mfma_f32_16x16x32_bf16 v[84:87], v[176:179], v[218:221], v[84:87]
	v_mfma_f32_16x16x32_bf16 v[80:83], v[184:187], v[218:221], v[80:83]
	v_mfma_f32_16x16x32_bf16 v[68:71], v[176:179], v[226:229], v[68:71]
	v_mfma_f32_16x16x32_bf16 v[64:67], v[184:187], v[226:229], v[64:67]
	s_barrier
	s_add_i32 s72, s72, s9
	v_lshl_add_u64 v[208:209], s[70:71], 0, v[210:211]
	s_mov_b32 m0, s72
	ds_read_b128 v[188:191], v143 offset:16384
	ds_read_b128 v[192:195], v143 offset:17408
	ds_read_b128 v[196:199], v143 offset:18432
	ds_read_b128 v[200:203], v143 offset:19456
	ds_read_b128 v[204:207], v143 offset:20480
	ds_read_b128 v[218:221], v143 offset:21504
	ds_read_b128 v[222:225], v143 offset:22528
	ds_read_b128 v[226:229], v143 offset:23552
	global_load_lds_dwordx4 v[208:209], off
	s_add_i32 m0, s72, 0x2000
	v_lshl_add_u64 v[230:231], s[70:71], 0, v[130:131]
	s_add_u32 s70, s70, s10
	s_addc_u32 s71, s71, s11
	s_add_i32 s69, s69, s9
	global_load_lds_dwordx4 v[230:231], off
	v_lshl_add_u64 v[232:233], s[70:71], 0, v[210:211]
	s_mov_b32 m0, s69
	v_lshl_add_u64 v[242:243], s[70:71], 0, v[130:131]
	global_load_lds_dwordx4 v[232:233], off
	s_add_i32 m0, s69, 0x2000
	v_lshl_add_u64 v[244:245], s[6:7], 0, v[134:135]
	global_load_lds_dwordx4 v[242:243], off
	s_mov_b32 m0, s13
	v_lshl_add_u64 v[246:247], s[6:7], 0, v[132:133]
	global_load_lds_dwordx4 v[244:245], off
	s_mov_b32 m0, s25
	s_nop 0
	global_load_lds_dwordx4 v[246:247], off
	s_waitcnt vmcnt(8)
	s_waitcnt lgkmcnt(0)
	s_barrier
; #define PG8_STAGE(bufoff, gbase, voff) do { _Pragma("unroll") for (int _i = 0; _i < 2; ++_i) \
;         __builtin_amdgcn_global_load_lds((const unsigned*)((const char*)(gbase) + (voff)[_i]), (PG8_LAS unsigned*)(lds + (bufoff) + ldsw + _i * 8192), 16, 0, 0); } while (0)
; #define PG8_LDA(dst, b, h) do { _Pragma("unroll") for (int m = 0; m < 4; ++m) _Pragma("unroll") for (int k = 0; k < 2; ++k) dst[m][k] = *(const PG8_LAS bf16x8*)(lds + PG8_SA(b, h) + aoff + m * 2048 + k * 1024); } while (0)
; #define PG8_LDB(dst, b, h) do { _Pragma("unroll") for (int n = 0; n < 2; ++n) _Pragma("unroll") for (int k = 0; k < 2; ++k) dst[n][k] = *(const PG8_LAS bf16x8*)(lds + PG8_SB(b, h) + boff + n * 2048 + k * 1024); } while (0)
; #define PG8_MMA(ai, bj, At, Bt) do { __builtin_amdgcn_s_setprio(1); _Pragma("unroll") for (int m = 0; m < 4; ++m) _Pragma("unroll") for (int n = 0; n < 2; ++n) _Pragma("unroll") for (int k = 0; k < 2; ++k) \
;         acc[ai][bj][m][n] = __builtin_amdgcn_mfma_f32_16x16x32_bf16(Bt[n][k], At[m][k], acc[ai][bj][m][n], 0, 0, 0); __builtin_amdgcn_s_setprio(0); } while (0)
; #define PG8_WAIT_V(n) asm volatile("s_waitcnt vmcnt(" #n ")" ::: "memory")
; #define PG8_WAIT_L(n) asm volatile("s_waitcnt lgkmcnt(" #n ")" ::: "memory")
; #define PG8_BAR __builtin_amdgcn_s_barrier()
; template <class Epi>
; __device__ __forceinline__ void gemm_phase(PG8_LAS unsigned char* lds, const Gemm g, const StaticOrder& S, const Epi& E, const int wave_s) {
;     ...
;             PG8_WAIT_V(8); PG8_WAIT_L(0); PG8_BAR; PG8_MMA(0, 0, At, B0); PG8_MMA(0, 1, At, B1); PG8_BAR; PG8_SCHED;
;             PG8_LDA(At, 0, 1); PG8_STAGE(PG8_SB(0, 0), b2, voffB); PG8_STAGE(PG8_SB(0, 1), b2 + hstepB, voffB); PG8_STAGE(PG8_SA(0, 0), a2, voffA);
;             PG8_WAIT_V(8); PG8_WAIT_L(0); PG8_BAR; PG8_MMA(1, 0, At, B0); PG8_MMA(1, 1, At, B1); PG8_BAR; PG8_SCHED;
;             PG8_LDB(B0, 1, 0); PG8_LDB(B1, 1, 1); PG8_SCHED; PG8_LDA(At, 1, 0); PG8_STAGE(PG8_SA(0, 1), a2 + hstepA, voffA);
;             PG8_WAIT_V(8); PG8_WAIT_L(0); PG8_BAR; PG8_MMA(0, 0, At, B0); PG8_MMA(0, 1, At, B1); PG8_BAR; PG8_SCHED;
;             PG8_LDA(At, 1, 1); PG8_STAGE(PG8_SB(1, 0), b3, voffB); PG8_STAGE(PG8_SB(1, 1), b3 + hstepB, voffB); PG8_STAGE(PG8_SA(1, 0), a3, voffA);
;             PG8_WAIT_V(8); PG8_WAIT_L(0); PG8_BAR; PG8_MMA(1, 0, At, B0); PG8_MMA(1, 1, At, B1); PG8_BAR; PG8_SCHED;
	s_waitcnt lgkmcnt(0)
	v_mfma_f32_16x16x32_bf16 v[60:63], v[156:159], v[188:191], v[60:63]
	v_mfma_f32_16x16x32_bf16 v[56:59], v[164:167], v[188:191], v[56:59]
	v_mfma_f32_16x16x32_bf16 v[44:47], v[156:159], v[196:199], v[44:47]
	v_mfma_f32_16x16x32_bf16 v[40:43], v[164:167], v[196:199], v[40:43]
	v_mfma_f32_16x16x32_bf16 v[28:31], v[156:159], v[204:207], v[28:31]
	v_mfma_f32_16x16x32_bf16 v[24:27], v[164:167], v[204:207], v[24:27]
	v_mfma_f32_16x16x32_bf16 v[12:15], v[156:159], v[222:225], v[12:15]
	v_mfma_f32_16x16x32_bf16 v[8:11], v[164:167], v[222:225], v[8:11]
	v_mfma_f32_16x16x32_bf16 v[60:63], v[160:163], v[192:195], v[60:63]
	v_mfma_f32_16x16x32_bf16 v[56:59], v[168:171], v[192:195], v[56:59]
	v_mfma_f32_16x16x32_bf16 v[44:47], v[160:163], v[200:203], v[44:47]
	v_mfma_f32_16x16x32_bf16 v[40:43], v[168:171], v[200:203], v[40:43]
	v_mfma_f32_16x16x32_bf16 v[28:31], v[160:163], v[218:221], v[28:31]
	v_mfma_f32_16x16x32_bf16 v[24:27], v[168:171], v[218:221], v[24:27]
	v_mfma_f32_16x16x32_bf16 v[12:15], v[160:163], v[226:229], v[12:15]
	v_mfma_f32_16x16x32_bf16 v[8:11], v[168:171], v[226:229], v[8:11]
	v_mfma_f32_16x16x32_bf16 v[52:55], v[172:175], v[188:191], v[52:55]
	v_mfma_f32_16x16x32_bf16 v[48:51], v[180:183], v[188:191], v[48:51]
	v_mfma_f32_16x16x32_bf16 v[36:39], v[172:175], v[196:199], v[36:39]
	v_mfma_f32_16x16x32_bf16 v[32:35], v[180:183], v[196:199], v[32:35]
	v_mfma_f32_16x16x32_bf16 v[20:23], v[172:175], v[204:207], v[20:23]
	v_mfma_f32_16x16x32_bf16 v[16:19], v[180:183], v[204:207], v[16:19]
	v_mfma_f32_16x16x32_bf16 v[4:7], v[172:175], v[222:225], v[4:7]
	v_mfma_f32_16x16x32_bf16 v[0:3], v[180:183], v[222:225], v[0:3]
	v_mfma_f32_16x16x32_bf16 v[52:55], v[176:179], v[192:195], v[52:55]
	v_mfma_f32_16x16x32_bf16 v[48:51], v[184:187], v[192:195], v[48:51]
	v_mfma_f32_16x16x32_bf16 v[36:39], v[176:179], v[200:203], v[36:39]
	v_mfma_f32_16x16x32_bf16 v[32:35], v[184:187], v[200:203], v[32:35]
	v_mfma_f32_16x16x32_bf16 v[20:23], v[176:179], v[218:221], v[20:23]
	v_mfma_f32_16x16x32_bf16 v[16:19], v[184:187], v[218:221], v[16:19]
	v_mfma_f32_16x16x32_bf16 v[4:7], v[176:179], v[226:229], v[4:7]
	v_mfma_f32_16x16x32_bf16 v[0:3], v[184:187], v[226:229], v[0:3]
	s_barrier
	s_add_i32 s69, 0, 0x18000
	v_add_u32_e32 v145, s69, v141
	s_add_i32 s70, 0, 0x1c000
	ds_read_b128 v[156:159], v145
	ds_read_b128 v[160:163], v145 offset:1024
	ds_read_b128 v[164:167], v145 offset:2048
	ds_read_b128 v[168:171], v145 offset:3072
	v_add_u32_e32 v145, s70, v141
	ds_read_b128 v[172:175], v145
	ds_read_b128 v[176:179], v145 offset:1024
	ds_read_b128 v[180:183], v145 offset:2048
	ds_read_b128 v[184:187], v145 offset:3072
	s_add_u32 s6, s6, s4
	s_addc_u32 s7, s7, s5
	s_mov_b32 m0, s27
	v_lshl_add_u64 v[248:249], s[6:7], 0, v[134:135]
	ds_read_b128 v[188:191], v143 offset:32768
	ds_read_b128 v[192:195], v143 offset:33792
	ds_read_b128 v[196:199], v143 offset:34816
	ds_read_b128 v[200:203], v143 offset:35840
	ds_read_b128 v[204:207], v143 offset:36864
	ds_read_b128 v[218:221], v143 offset:37888
	ds_read_b128 v[222:225], v143 offset:38912
	ds_read_b128 v[226:229], v143 offset:39936
	global_load_lds_dwordx4 v[248:249], off
	v_lshl_add_u64 v[248:249], s[6:7], 0, v[132:133]
	s_mov_b32 m0, s38
	s_nop 0
	global_load_lds_dwordx4 v[248:249], off
	s_waitcnt vmcnt(8)
	s_waitcnt lgkmcnt(0)
	s_barrier
	s_waitcnt lgkmcnt(0)
	v_mfma_f32_16x16x32_bf16 v[126:129], v[156:159], v[188:191], v[126:129]
	v_mfma_f32_16x16x32_bf16 v[122:125], v[164:167], v[188:191], v[122:125]
	v_mfma_f32_16x16x32_bf16 v[110:113], v[156:159], v[196:199], v[110:113]
	v_mfma_f32_16x16x32_bf16 v[106:109], v[164:167], v[196:199], v[106:109]
	v_mfma_f32_16x16x32_bf16 v[92:95], v[156:159], v[204:207], v[92:95]
	v_mfma_f32_16x16x32_bf16 v[88:91], v[164:167], v[204:207], v[88:91]
	v_mfma_f32_16x16x32_bf16 v[76:79], v[156:159], v[222:225], v[76:79]
	v_mfma_f32_16x16x32_bf16 v[72:75], v[164:167], v[222:225], v[72:75]
	v_mfma_f32_16x16x32_bf16 v[126:129], v[160:163], v[192:195], v[126:129]
	v_mfma_f32_16x16x32_bf16 v[122:125], v[168:171], v[192:195], v[122:125]
	v_mfma_f32_16x16x32_bf16 v[110:113], v[160:163], v[200:203], v[110:113]
	v_mfma_f32_16x16x32_bf16 v[106:109], v[168:171], v[200:203], v[106:109]
	v_mfma_f32_16x16x32_bf16 v[92:95], v[160:163], v[218:221], v[92:95]
	v_mfma_f32_16x16x32_bf16 v[88:91], v[168:171], v[218:221], v[88:91]
	v_mfma_f32_16x16x32_bf16 v[76:79], v[160:163], v[226:229], v[76:79]
	v_mfma_f32_16x16x32_bf16 v[72:75], v[168:171], v[226:229], v[72:75]
	v_mfma_f32_16x16x32_bf16 v[118:121], v[172:175], v[188:191], v[118:121]
	v_mfma_f32_16x16x32_bf16 v[114:117], v[180:183], v[188:191], v[114:117]
	v_mfma_f32_16x16x32_bf16 v[102:105], v[172:175], v[196:199], v[102:105]
	v_mfma_f32_16x16x32_bf16 v[98:101], v[180:183], v[196:199], v[98:101]
	v_mfma_f32_16x16x32_bf16 v[84:87], v[172:175], v[204:207], v[84:87]
	v_mfma_f32_16x16x32_bf16 v[80:83], v[180:183], v[204:207], v[80:83]
	v_mfma_f32_16x16x32_bf16 v[68:71], v[172:175], v[222:225], v[68:71]
	v_mfma_f32_16x16x32_bf16 v[64:67], v[180:183], v[222:225], v[64:67]
	v_mfma_f32_16x16x32_bf16 v[118:121], v[176:179], v[192:195], v[118:121]
	v_mfma_f32_16x16x32_bf16 v[114:117], v[184:187], v[192:195], v[114:117]
	v_mfma_f32_16x16x32_bf16 v[102:105], v[176:179], v[200:203], v[102:105]
	v_mfma_f32_16x16x32_bf16 v[98:101], v[184:187], v[200:203], v[98:101]
	v_mfma_f32_16x16x32_bf16 v[84:87], v[176:179], v[218:221], v[84:87]
	v_mfma_f32_16x16x32_bf16 v[80:83], v[184:187], v[218:221], v[80:83]
	v_mfma_f32_16x16x32_bf16 v[68:71], v[176:179], v[226:229], v[68:71]
	v_mfma_f32_16x16x32_bf16 v[64:67], v[184:187], v[226:229], v[64:67]
	s_barrier
; __device__ __forceinline__ int fresh_tid(int wave_s) { unsigned z = 0; asm volatile("" : "+v"(z)); return wave_s * 64 + (int)__builtin_amdgcn_mbcnt_hi(~0u, __builtin_amdgcn_mbcnt_lo(~0u, z)); }
; #define PG8_STAGE(bufoff, gbase, voff) do { _Pragma("unroll") for (int _i = 0; _i < 2; ++_i) \
;         __builtin_amdgcn_global_load_lds((const unsigned*)((const char*)(gbase) + (voff)[_i]), (PG8_LAS unsigned*)(lds + (bufoff) + ldsw + _i * 8192), 16, 0, 0); } while (0)
; #define PG8_LDA(dst, b, h) do { _Pragma("unroll") for (int m = 0; m < 4; ++m) _Pragma("unroll") for (int k = 0; k < 2; ++k) dst[m][k] = *(const PG8_LAS bf16x8*)(lds + PG8_SA(b, h) + aoff + m * 2048 + k * 1024); } while (0)
; #define PG8_MMA(ai, bj, At, Bt) do { __builtin_amdgcn_s_setprio(1); _Pragma("unroll") for (int m = 0; m < 4; ++m) _Pragma("unroll") for (int n = 0; n < 2; ++n) _Pragma("unroll") for (int k = 0; k < 2; ++k) \
;         acc[ai][bj][m][n] = __builtin_amdgcn_mfma_f32_16x16x32_bf16(Bt[n][k], At[m][k], acc[ai][bj][m][n], 0, 0, 0); __builtin_amdgcn_s_setprio(0); } while (0)
; #define PG8_WAIT_V(n) asm volatile("s_waitcnt vmcnt(" #n ")" ::: "memory")
; #define PG8_WAIT_L(n) asm volatile("s_waitcnt lgkmcnt(" #n ")" ::: "memory")
; #define PG8_BAR __builtin_amdgcn_s_barrier()
; #define PG8_SCHED __builtin_amdgcn_sched_barrier(0)
; template <class Epi>
; __device__ __forceinline__ void gemm_phase(PG8_LAS unsigned char* lds, const Gemm g, const StaticOrder& S, const Epi& E, const int wave_s) {
;     ...
;             PG8_WAIT_V(8); PG8_WAIT_L(0); PG8_BAR; PG8_MMA(0, 0, At, B0); PG8_MMA(0, 1, At, B1); PG8_BAR; PG8_SCHED;
;             PG8_LDA(At, 1, 1); PG8_STAGE(PG8_SB(1, 0), b3, voffB); PG8_STAGE(PG8_SB(1, 1), b3 + hstepB, voffB); PG8_STAGE(PG8_SA(1, 0), a3, voffA);
;             PG8_WAIT_V(8); PG8_WAIT_L(0); PG8_BAR; PG8_MMA(1, 0, At, B0); PG8_MMA(1, 1, At, B1); PG8_BAR; PG8_SCHED;
;         }
;         if (wr == 0) PG8_BAR;
;         { const int tl = fresh_tid(wave_s); const int w2 = wave_s, l2 = tl & 63;
;           E(acc, cur, w2 >> 2, w2 & 3, l2 & 15, l2 >> 4, pre); }
;         if (!has_next) break;
	s_add_i32 s6, s69, s9
	v_lshl_add_u64 v[208:209], v[208:209], 0, s[52:53]
	s_mov_b32 m0, s6
	ds_read_b128 v[188:191], v143 offset:49152
	ds_read_b128 v[192:195], v143 offset:50176
	ds_read_b128 v[196:199], v143 offset:51200
	ds_read_b128 v[200:203], v143 offset:52224
	ds_read_b128 v[204:207], v143 offset:53248
	ds_read_b128 v[218:221], v143 offset:54272
	ds_read_b128 v[222:225], v143 offset:55296
	ds_read_b128 v[226:229], v143 offset:56320
	global_load_lds_dwordx4 v[208:209], off
	v_lshl_add_u64 v[208:209], v[230:231], 0, s[52:53]
	s_add_i32 m0, s6, 0x2000
	s_add_i32 s6, s70, s9
	global_load_lds_dwordx4 v[208:209], off
	v_lshl_add_u64 v[208:209], v[232:233], 0, s[52:53]
	s_mov_b32 m0, s6
	s_nop 0
	global_load_lds_dwordx4 v[208:209], off
	v_lshl_add_u64 v[208:209], v[242:243], 0, s[52:53]
	s_add_i32 m0, s6, 0x2000
	s_nop 0
	global_load_lds_dwordx4 v[208:209], off
	v_lshl_add_u64 v[208:209], v[244:245], 0, s[52:53]
	s_mov_b32 m0, s39
	s_nop 0
	global_load_lds_dwordx4 v[208:209], off
	v_lshl_add_u64 v[208:209], v[246:247], 0, s[52:53]
	s_mov_b32 m0, s58
	s_nop 0
	global_load_lds_dwordx4 v[208:209], off
	s_waitcnt vmcnt(8)
	s_waitcnt lgkmcnt(0)
	s_barrier
	s_waitcnt lgkmcnt(0)
	v_mfma_f32_16x16x32_bf16 v[60:63], v[156:159], v[188:191], v[60:63]
	v_mfma_f32_16x16x32_bf16 v[56:59], v[164:167], v[188:191], v[56:59]
	v_mfma_f32_16x16x32_bf16 v[44:47], v[156:159], v[196:199], v[44:47]
	v_mfma_f32_16x16x32_bf16 v[40:43], v[164:167], v[196:199], v[40:43]
	v_mfma_f32_16x16x32_bf16 v[28:31], v[156:159], v[204:207], v[28:31]
	v_mfma_f32_16x16x32_bf16 v[24:27], v[164:167], v[204:207], v[24:27]
	v_mfma_f32_16x16x32_bf16 v[12:15], v[156:159], v[222:225], v[12:15]
	v_mfma_f32_16x16x32_bf16 v[8:11], v[164:167], v[222:225], v[8:11]
	v_mfma_f32_16x16x32_bf16 v[60:63], v[160:163], v[192:195], v[60:63]
	v_mfma_f32_16x16x32_bf16 v[56:59], v[168:171], v[192:195], v[56:59]
	v_mfma_f32_16x16x32_bf16 v[44:47], v[160:163], v[200:203], v[44:47]
	v_mfma_f32_16x16x32_bf16 v[40:43], v[168:171], v[200:203], v[40:43]
	v_mfma_f32_16x16x32_bf16 v[28:31], v[160:163], v[218:221], v[28:31]
	v_mfma_f32_16x16x32_bf16 v[24:27], v[168:171], v[218:221], v[24:27]
	v_mfma_f32_16x16x32_bf16 v[12:15], v[160:163], v[226:229], v[12:15]
	v_mfma_f32_16x16x32_bf16 v[8:11], v[168:171], v[226:229], v[8:11]
	v_mfma_f32_16x16x32_bf16 v[52:55], v[172:175], v[188:191], v[52:55]
	v_mfma_f32_16x16x32_bf16 v[48:51], v[180:183], v[188:191], v[48:51]
	v_mfma_f32_16x16x32_bf16 v[36:39], v[172:175], v[196:199], v[36:39]
	v_mfma_f32_16x16x32_bf16 v[32:35], v[180:183], v[196:199], v[32:35]
	v_mfma_f32_16x16x32_bf16 v[20:23], v[172:175], v[204:207], v[20:23]
	v_mfma_f32_16x16x32_bf16 v[16:19], v[180:183], v[204:207], v[16:19]
	v_mfma_f32_16x16x32_bf16 v[4:7], v[172:175], v[222:225], v[4:7]
	v_mfma_f32_16x16x32_bf16 v[0:3], v[180:183], v[222:225], v[0:3]
	v_mfma_f32_16x16x32_bf16 v[52:55], v[176:179], v[192:195], v[52:55]
	v_mfma_f32_16x16x32_bf16 v[48:51], v[184:187], v[192:195], v[48:51]
	v_mfma_f32_16x16x32_bf16 v[36:39], v[176:179], v[200:203], v[36:39]
	v_mfma_f32_16x16x32_bf16 v[32:35], v[184:187], v[200:203], v[32:35]
	v_mfma_f32_16x16x32_bf16 v[20:23], v[176:179], v[218:221], v[20:23]
	v_mfma_f32_16x16x32_bf16 v[16:19], v[184:187], v[218:221], v[16:19]
	v_mfma_f32_16x16x32_bf16 v[4:7], v[176:179], v[226:229], v[4:7]
	v_mfma_f32_16x16x32_bf16 v[0:3], v[184:187], v[226:229], v[0:3]
	s_barrier
	s_add_u32 s56, s56, 0x100
	s_addc_u32 s57, s57, 0
	s_add_u32 s66, s66, 0x100
	s_addc_u32 s67, s67, 0
	s_cmp_ge_i32 s68, s59
	s_mov_b32 s6, s68
	s_cbranch_scc0 .LBB0_950
.LBB0_951:
	s_setprio 0
	s_and_b64 vcc, exec, s[48:49]
	s_cbranch_vccz .LBB0_953
	s_barrier
